# v35 plus scalar-base K/V staging loads in attention and the counted vmcnt wait in the HGRN chunk loop (both bit-identical)
# speedup vs baseline: 1.0019x; 1.0019x over previous
.LBB0_231:
	s_bitcmp1_b32 s40, 0
	s_cselect_b32 s43, 0x8800, 0
	s_cmp_lt_u32 s97, 4
	s_cbranch_scc1 .Latt_top_done
	s_add_i32 s0, s40, -1
	s_cmp_ge_u32 s0, s38
	s_cbranch_scc1 .Latt_top_done
	s_sub_i32 s0, 0, s43
	v_add_u32_e32 v238, s0, v175
	s_waitcnt vmcnt(1)
	ds_write_b128 v238, v[124:127] offset:34816
	ds_write_b128 v238, v[116:119] offset:43520
	v_add_u32_e32 v238, s0, v176
	s_cmp_ge_u32 s40, s38
	s_waitcnt vmcnt(0)
	ds_write_b128 v238, v[140:143] offset:52224
	ds_write_b128 v238, v[132:135] offset:60928
	s_cbranch_scc1 .Latt_top_done
	s_add_u32 s14, s22, 0x14400000
	s_addc_u32 s15, s23, 0
	global_load_dwordx4 v[124:127], v144, s[14:15]
	global_load_dwordx4 v[116:119], v144, s[14:15] offset:256
	global_load_dwordx4 v[140:143], v162, s[14:15]
	s_add_u32 s14, s14, 0xc0000
	s_addc_u32 s15, s15, 0
	global_load_dwordx4 v[132:135], v162, s[14:15]

.LBB0_236:
	s_cmp_ge_u32 s97, 4
	s_cbranch_scc1 .LBB0_238
	s_sub_i32 s0, 0, s43
	v_add_u32_e32 v166, s0, v175
	s_waitcnt vmcnt(1)
	ds_write_b128 v166, v[124:127] offset:34816
	ds_write_b128 v166, v[116:119] offset:43520
	v_add_u32_e32 v166, s0, v176
	s_cmp_ge_u32 s40, s38
	s_waitcnt vmcnt(0)
	ds_write_b128 v166, v[140:143] offset:52224
	ds_write_b128 v166, v[132:135] offset:60928
	s_cbranch_scc1 .LBB0_238
	s_add_u32 s14, s22, 0x14400000
	s_addc_u32 s15, s23, 0
	global_load_dwordx4 v[124:127], v144, s[14:15]
	global_load_dwordx4 v[116:119], v144, s[14:15] offset:256
	global_load_dwordx4 v[140:143], v162, s[14:15]
	s_add_u32 s14, s14, 0xc0000
	s_addc_u32 s15, s15, 0
	global_load_dwordx4 v[132:135], v162, s[14:15]
